# v52: scalar fetch of the program entry at each step head, layer-1 adaLN moved to the idle workgroups of step 3 so that the norm after FFN-down 1 is chained too (9 chained norms)
# speedup vs baseline: 1.0559x; 1.0102x over previous
.LBB0_9:
	s_mul_i32 s3, s6, 3
	s_getpc_b64 s[0:1]
	s_add_u32 s0, s0, PROG@rel32@lo+4
	s_addc_u32 s1, s1, PROG@rel32@hi+12
	s_and_b32 s2, s3, -4
	s_add_u32 s0, s0, s2
	s_addc_u32 s1, s1, 0
	s_load_dwordx2 s[0:1], s[0:1], 0x0
	s_and_b32 s3, s3, 3
	s_lshl_b32 s3, s3, 3
	s_waitcnt lgkmcnt(0)
	s_lshr_b64 s[0:1], s[0:1], s3
	s_and_b32 s2, s0, 0xffff
	v_mov_b32_e32 v0, s2
	s_bfe_u32 s2, s0, 0x80010
	v_mov_b32_e32 v2, s2
	s_mov_b32 s7, s63
	v_writelane_b32 v254, s6, 61
	s_mov_b32 s67, s66
	s_mov_b64 s[8:9], -1
	v_writelane_b32 v254, s7, 62
	s_waitcnt vmcnt(0) lgkmcnt(0)
	v_lshrrev_b32_e32 v3, 8, v0
	v_readlane_b32 s0, v254, 4
	v_readlane_b32 s60, v254, 0
	v_readlane_b32 s61, v254, 1
	v_writelane_b32 v254, s0, 63
	s_waitcnt vmcnt(0)
	v_readfirstlane_b32 s0, v2
	s_load_dwordx4 s[16:19], s[60:61], 0x108
	s_add_u32 s10, s60, 0x108
	v_writelane_b32 v255, s0, 0
	s_mov_b64 s[0:1], 0
	v_writelane_b32 v255, s0, 1
	s_addc_u32 s11, s61, 0
	v_and_b32_e32 v0, 0xff, v0
	v_writelane_b32 v255, s1, 2
	v_writelane_b32 v255, s10, 3
	v_readfirstlane_b32 s2, v0
	v_readfirstlane_b32 s80, v3
	v_writelane_b32 v255, s11, 4
	s_waitcnt lgkmcnt(0)
	s_add_u32 s10, s18, 0xb800000
	v_writelane_b32 v255, s16, 5
	s_addc_u32 s11, s19, 0
	s_cmp_lt_i32 s2, 9
	v_writelane_b32 v255, s17, 6
	v_writelane_b32 v255, s18, 7
	v_writelane_b32 v255, s19, 8
	v_writelane_b32 v255, s10, 9
	s_nop 1
	v_writelane_b32 v255, s11, 10
	v_writelane_b32 v255, s2, 11
	s_mov_b64 s[2:3], 0
	v_writelane_b32 v255, s2, 12
	s_nop 1
	v_writelane_b32 v255, s3, 13
	s_mov_b64 s[2:3], 0
	s_cbranch_scc1 .LBB0_142
	v_readlane_b32 s0, v255, 11
	s_cmp_gt_i32 s0, 12
	s_cbranch_scc0 .LBB0_17
	v_writelane_b32 v255, s2, 16
	s_cmp_gt_i32 s0, 14
	s_mov_b64 s[22:23], -1
	v_writelane_b32 v255, s3, 17
	s_mov_b64 s[0:1], 0
	v_writelane_b32 v255, s0, 12
	s_mov_b64 s[2:3], 0
	s_mov_b64 s[6:7], -1
	v_writelane_b32 v255, s1, 13
	s_cbranch_scc0 .LBB0_113
	s_mov_b64 s[0:1], 0
	v_writelane_b32 v255, s0, 12
	s_nop 1
	v_writelane_b32 v255, s1, 13
	s_nop 0
	v_readlane_b32 s0, v255, 11
	s_cmp_gt_i32 s0, 15
	s_cbranch_scc0 .LBB0_111
	v_readlane_b32 s0, v255, 11
	s_cmp_gt_i32 s0, 16
	s_mov_b64 s[2:3], -1
	s_cbranch_scc0 .LBB0_28
	s_cmp_eq_u32 s0, 17
	s_cbranch_scc0 .LBB0_27
	s_lshl_b32 s0, s67, 3
	v_readlane_b32 s1, v254, 63
	s_add_i32 s6, s0, s1
	v_mov_b32_e32 v0, v1
	s_cmpk_gt_i32 s6, 0x2fff
	s_cbranch_scc1 .LBB0_27
	v_mbcnt_lo_u32_b32 v0, -1, v0
	s_load_dwordx2 s[0:1], s[60:61], 0x60
	v_mbcnt_hi_u32_b32 v0, -1, v0
	v_lshlrev_b32_e32 v18, 2, v0
	v_ashrrev_i32_e32 v19, 31, v18
	v_lshlrev_b64 v[20:21], 2, v[18:19]
	s_waitcnt lgkmcnt(0)
	v_lshl_add_u64 v[14:15], s[0:1], 0, v[20:21]
	global_load_dwordx4 v[2:5], v[14:15], off
	global_load_dwordx4 v[6:9], v[14:15], off offset:1024
	global_load_dwordx4 v[10:13], v[14:15], off offset:2048
	s_nop 0
	global_load_dwordx4 v[14:17], v[14:15], off offset:3072
	s_load_dwordx4 s[0:3], s[60:61], 0x108
	v_xor_b32_e32 v0, 4, v18
	v_xor_b32_e32 v70, 8, v18
	v_xor_b32_e32 v71, 16, v18
	v_xor_b32_e32 v72, 32, v18
	s_waitcnt lgkmcnt(0)
	v_lshl_add_u64 v[66:67], s[0:1], 0, v[20:21]
	v_xor_b32_e32 v73, 64, v18
	v_xor_b32_e32 v74, 0x80, v18
	s_branch .LBB0_19

.LBB0_893:
	s_cmpk_lt_i32 s67, 192
	s_cbranch_scc1 .Ladh_skip
	v_readlane_b32 s1, v254, 61
	s_mov_b32 s20, 0
	s_cmp_eq_u32 s1, 3
	s_cselect_b32 s20, 1, s20
	s_cmp_eq_u32 s1, 14
	s_cselect_b32 s20, 2, s20
	s_cmp_eq_u32 s1, 22
	s_cselect_b32 s20, 3, s20
	s_cmp_eq_u32 s20, 0
	s_cbranch_scc1 .Ladh_skip
	v_readlane_b32 s0, v254, 63
	s_sub_i32 s3, s67, 192
	s_load_dwordx4 s[8:11], s[60:61], 0x38
	s_load_dwordx4 s[12:15], s[60:61], 0x48
	v_mbcnt_lo_u32_b32 v0, -1, 0
	v_mbcnt_hi_u32_b32 v0, -1, v0
	s_lshl_b32 s16, s0, 14
	s_lshl_b32 s1, s0, 9
	v_lshl_add_u32 v18, v0, 2, s1
	v_lshl_add_u32 v19, v0, 4, s16
	s_waitcnt lgkmcnt(0)
	s_add_u32 s6, s8, 0x1000
	s_addc_u32 s7, s9, 0
	global_load_dword v26, v18, s[10:11]
	global_load_dword v27, v18, s[10:11] offset:256
	global_load_dword v28, v18, s[8:9]
	global_load_dword v29, v18, s[8:9] offset:256
	global_load_dword v30, v18, s[6:7]
	global_load_dword v31, v18, s[6:7] offset:256
	s_waitcnt vmcnt(0)
	v_mul_f32_e32 v74, 0xbfb8aa3b, v26
	v_mul_f32_e32 v75, 0xbfb8aa3b, v27
	v_mul_f32_e32 v76, 0xbfb8aa3b, v28
	v_mul_f32_e32 v77, 0xbfb8aa3b, v29
	v_mul_f32_e32 v78, 0xbfb8aa3b, v30
	v_mul_f32_e32 v79, 0xbfb8aa3b, v31
	v_exp_f32_e32 v74, v74
	v_exp_f32_e32 v75, v75
	v_exp_f32_e32 v76, v76
	v_exp_f32_e32 v77, v77
	v_exp_f32_e32 v78, v78
	v_exp_f32_e32 v79, v79
	v_add_f32_e32 v74, 1.0, v74
	v_add_f32_e32 v75, 1.0, v75
	v_add_f32_e32 v76, 1.0, v76
	v_add_f32_e32 v77, 1.0, v77
	v_add_f32_e32 v78, 1.0, v78
	v_add_f32_e32 v79, 1.0, v79
	v_rcp_f32_e32 v74, v74
	v_rcp_f32_e32 v75, v75
	v_rcp_f32_e32 v76, v76
	v_rcp_f32_e32 v77, v77
	v_rcp_f32_e32 v78, v78
	v_rcp_f32_e32 v79, v79
	v_mul_f32_e32 v26, v26, v74
	v_mul_f32_e32 v27, v27, v75
	v_mul_f32_e32 v28, v28, v76
	v_mul_f32_e32 v29, v29, v77
	v_mul_f32_e32 v30, v30, v78
	v_mul_f32_e32 v31, v31, v79
	v_mov_b32_e32 v90, v26
	v_mov_b32_e32 v91, v28
	v_mov_b32_e32 v92, v30
	v_mov_b32_e32 v93, 0
	v_mov_b32_e32 v94, v27
	v_mov_b32_e32 v95, v29
	v_mov_b32_e32 v96, v31
	v_mov_b32_e32 v97, 0
	ds_write_b128 v19, v[90:93]
	ds_write_b128 v19, v[94:97] offset:1024
	v_lshrrev_b32_e32 v20, 3, v0
	v_and_b32_e32 v21, 7, v0
	v_mul_u32_u24_e32 v22, 0x9000, v20
	v_lshl_add_u32 v22, v21, 4, v22
	s_mul_i32 s17, s0, 0x480000
	s_mul_i32 s1, s20, 0x2400000
	s_add_u32 s17, s17, s1
	s_add_u32 s12, s12, s17
	s_addc_u32 s13, s13, 0
	s_mul_i32 s1, s20, 0x9000
	s_add_u32 s14, s14, s1
	s_addc_u32 s15, s15, 0
	v_lshl_add_u32 v23, v20, 4, s16
	s_mul_i32 s17, s0, 0x180
	s_add_i32 s17, s17, 131072
	v_readlane_b32 s8, v255, 7
	v_readlane_b32 s9, v255, 8
	s_mul_i32 s1, s20, 0x1b000
	s_add_i32 s1, s1, 0x100000
	s_add_u32 s8, s8, s1
	s_addc_u32 s9, s9, 0
	s_mov_b32 s18, s3
	s_waitcnt lgkmcnt(0)
	v_lshl_add_u32 v94, v21, 4, s17
	s_mov_b32 s17, 131072
	v_lshl_add_u32 v95, v0, 2, s17
	v_lshlrev_b32_e32 v96, 2, v0

.LBB0_899:
	s_andn2_b64 vcc, exec, s[68:69]
	s_cbranch_vccnz .LBB0_1130
	v_readlane_b32 s0, v255, 11
	s_cmp_gt_i32 s0, 0
	s_mov_b64 s[2:3], -1
	s_cbranch_scc0 .LBB0_1013
	s_mov_b32 s0, s67
	s_mov_b32 s79, s0
	s_lshl_b32 s1, s0, 3
	v_readlane_b32 s0, v254, 63
	v_writelane_b32 v255, s58, 22
	s_add_i32 s1, s1, s0
	s_mov_b32 s67, 0x7f800000
	v_writelane_b32 v255, s59, 23
	v_mov_b32_e32 v0, v1
	s_cmpk_gt_i32 s1, 0x7ff
	s_cbranch_scc1 .LBB0_1012
	s_mov_b32 s100, s80
	s_ashr_i32 s0, s80, 2
	s_and_b32 s8, s80, 3
	s_cmp_eq_u32 s80, 1
	v_readlane_b32 s10, v255, 14
	s_cselect_b64 s[56:57], -1, 0
	s_or_b32 s2, s8, s0
	v_readlane_b32 s11, v255, 15
	s_cmp_lg_u32 s2, 0
	s_load_dwordx2 s[2:3], s[10:11], 0x58
	s_mul_i32 s0, s0, 3
	s_cselect_b64 s[94:95], -1, 0
	s_add_i32 s6, s0, s8
	s_ashr_i32 s7, s6, 31
	s_lshl_b64 s[6:7], s[6:7], 12
	s_waitcnt lgkmcnt(0)
	s_add_u32 s2, s2, s6
	s_addc_u32 s3, s3, s7
	v_mbcnt_lo_u32_b32 v0, -1, v0
	s_add_u32 s70, s10, 8
	v_mbcnt_hi_u32_b32 v92, -1, v0
	s_addc_u32 s71, s11, 0
	s_mulk_i32 s8, 0x3000
	v_readlane_b32 s6, v255, 22
	s_mul_i32 s80, s1, 6
	v_lshlrev_b32_e32 v94, 3, v92
	s_add_u32 s1, s6, s8
	v_ashrrev_i32_e32 v93, 31, v92
	v_readlane_b32 s8, v255, 5
	v_ashrrev_i32_e32 v95, 31, v94
	s_waitcnt vmcnt(0)
	v_lshlrev_b64 v[4:5], 2, v[92:93]
	v_readlane_b32 s10, v255, 7
	v_readlane_b32 s11, v255, 8
	v_lshl_add_u64 v[100:101], v[94:95], 2, s[2:3]
	v_lshlrev_b64 v[102:103], 5, v[94:95]
	v_lshl_add_u64 v[6:7], s[10:11], 0, v[4:5]
	s_mov_b64 s[10:11], 0x200000
	s_mov_b64 s[2:3], 0x4000
	v_readlane_b32 s7, v255, 23
	v_lshl_add_u64 v[98:99], v[6:7], 0, s[10:11]
	v_or_b32_e32 v6, 4, v94
	v_lshl_add_u64 v[104:105], v[102:103], 0, s[2:3]
	s_mov_b64 s[2:3], 0x4040
	s_addc_u32 s54, s7, 0
	v_ashrrev_i32_e32 v7, 31, v6
	v_lshl_add_u64 v[114:115], v[102:103], 0, s[2:3]
	s_mov_b64 s[2:3], 0x40c0
	s_ashr_i32 s81, s80, 31
	v_readlane_b32 s6, v255, 9
	v_lshlrev_b32_e32 v0, 2, v92
	v_add_u32_e32 v106, 0x204, v94
	v_or_b32_e32 v8, 2, v94
	v_lshlrev_b64 v[110:111], 5, v[6:7]
	v_or_b32_e32 v6, 6, v94
	v_lshl_add_u64 v[118:119], v[102:103], 0, s[2:3]
	s_lshl_b64 s[2:3], s[80:81], 6
	v_lshlrev_b64 v[2:3], 1, v[94:95]
	v_readlane_b32 s7, v255, 10
	v_xor_b32_e32 v126, 4, v0
	v_xor_b32_e32 v127, 8, v0
	v_xor_b32_e32 v128, 16, v0
	v_xor_b32_e32 v129, 32, v0
	v_xor_b32_e32 v130, 64, v0
	v_xor_b32_e32 v131, 0x80, v0
	v_and_b32_e32 v0, 4, v92
	v_ashrrev_i32_e32 v107, 31, v106
	v_ashrrev_i32_e32 v9, 31, v8
	v_ashrrev_i32_e32 v7, 31, v6
	v_lshl_add_u64 v[120:121], s[2:3], 0, v[4:5]
	s_lshl_b64 s[2:3], s[80:81], 11
	v_lshl_add_u64 v[96:97], s[6:7], 0, v[2:3]
	v_cmp_gt_i32_e64 s[6:7], 16, v92
	v_cmp_ne_u32_e64 s[74:75], 0, v0
	v_lshlrev_b64 v[108:109], 5, v[8:9]
	v_lshlrev_b64 v[112:113], 5, v[6:7]
	v_lshlrev_b64 v[116:117], 5, v[106:107]
	v_cmp_eq_u32_e64 s[68:69], 15, v92
	v_cmp_eq_u32_e64 s[12:13], 14, v92
	v_cmp_eq_u32_e64 s[14:15], 13, v92
	v_cmp_eq_u32_e64 s[16:17], 12, v92
	v_cmp_eq_u32_e64 s[18:19], 11, v92
	v_cmp_eq_u32_e64 s[20:21], 10, v92
	v_cmp_eq_u32_e64 s[22:23], 9, v92
	v_cmp_eq_u32_e64 s[24:25], 8, v92
	v_cmp_eq_u32_e64 s[26:27], 7, v92
	v_cmp_eq_u32_e64 s[28:29], 6, v92
	v_cmp_eq_u32_e64 s[30:31], 5, v92
	v_cmp_eq_u32_e64 s[34:35], 4, v92
	v_cmp_eq_u32_e64 s[36:37], 3, v92
	v_cmp_eq_u32_e64 s[38:39], 2, v92
	v_cmp_eq_u32_e64 s[40:41], 1, v92
	v_cmp_eq_u32_e64 s[42:43], 0, v92
	v_lshl_add_u64 v[122:123], s[2:3], 0, v[2:3]
	v_readlane_b32 s9, v255, 6
	s_cmp_lt_u32 s100, 2
	s_cbranch_scc1 .Lfn_old
	s_cmpk_gt_i32 s79, 191
	s_cbranch_scc1 .LBB0_1012
	s_and_b32 s0, s79, 7
	s_mul_i32 s0, s0, 6
	s_lshr_b32 s1, s79, 3
	s_mul_i32 s2, s1, 43
	s_lshr_b32 s2, s2, 8
	s_mul_i32 s3, s2, 6
	s_sub_i32 s1, s1, s3
	s_add_i32 s0, s0, s1
	s_lshl_b32 s80, s0, 8
	s_lshl_b32 s2, s2, 6
	s_add_i32 s80, s80, s2
	v_readlane_b32 s3, v254, 63
	s_lshl_b32 s2, s3, 3
	s_add_i32 s80, s80, s2
	s_mov_b32 s81, 0
	v_readlane_b32 s1, v254, 61
	s_add_i32 s1, s1, -1
	s_lshl_b32 s1, s1, 8
	s_lshl_b32 s0, s0, 2
	s_add_i32 s0, s0, s1
	s_add_i32 s0, s0, 0x10000
	v_readlane_b32 s22, v255, 7
	v_readlane_b32 s23, v255, 8
	s_add_u32 s22, s22, s0
	s_addc_u32 s23, s23, 0
	s_sub_i32 s1, s80, 0x1800
	s_max_i32 s1, s1, 0
	s_lshr_b32 s1, s1, 11
	s_ashr_i32 s0, s100, 2
	s_and_b32 s6, s100, 3
	s_mul_i32 s7, s0, 3
	s_add_i32 s8, s7, s6
	v_readlane_b32 s10, v255, 14
	v_readlane_b32 s11, v255, 15
	s_load_dwordx2 s[12:13], s[10:11], 0x58
	s_add_i32 s9, s7, s1
	s_mul_i32 s9, s9, 0x9000
	s_mul_i32 s14, s6, 0x3000
	s_add_i32 s9, s9, s14
	s_add_i32 s9, s9, 0x100000
	v_readlane_b32 s20, v255, 7
	v_readlane_b32 s21, v255, 8
	s_add_u32 s20, s20, s9
	s_addc_u32 s21, s21, 0
	v_lshlrev_b32_e32 v82, 5, v92
	v_lshlrev_b32_e32 v83, 4, v92
	s_lshl_b32 s8, s8, 12
	s_add_u32 s26, s20, 0x1000
	s_addc_u32 s27, s21, 0
	s_waitcnt lgkmcnt(0)
	s_add_u32 s12, s12, s8
	s_addc_u32 s13, s13, 0
	global_load_dwordx4 v[148:151], v82, s[12:13] offset:0
	global_load_dwordx4 v[170:173], v82, s[26:27] offset:0
	global_load_dwordx4 v[186:189], v82, s[20:21] offset:0
	global_load_dwordx4 v[152:155], v82, s[12:13] offset:16
	global_load_dwordx4 v[174:177], v82, s[26:27] offset:16
	global_load_dwordx4 v[190:193], v82, s[20:21] offset:16
	global_load_dwordx4 v[156:159], v82, s[12:13] offset:2048
	global_load_dwordx4 v[178:181], v82, s[26:27] offset:2048
	global_load_dwordx4 v[194:197], v82, s[20:21] offset:2048
	global_load_dwordx4 v[160:163], v82, s[12:13] offset:2064
	global_load_dwordx4 v[182:185], v82, s[26:27] offset:2064
	global_load_dwordx4 v[198:201], v82, s[20:21] offset:2064
	s_cmp_lg_u32 s3, 0
	s_cbranch_scc1 .Lfn_bar
	s_mov_b32 s2, 0

PROG:
	.byte	0, 0, 1
	.byte	1, 0, 1
	.byte	3, 0, 1
	.byte	4, 0, 1
	.byte	1, 1, 1
	.byte	5, 0, 1
	.byte	6, 0, 1
	.byte	7, 0, 1
	.byte	8, 0, 0
	.byte	1, 2, 1
	.byte	3, 1, 1
	.byte	4, 1, 0
	.byte	1, 4, 1
	.byte	3, 2, 1
	.byte	4, 2, 1
	.byte	2, 5, 1
	.byte	9, 0, 0
	.byte	10, 0, 1
	.byte	11, 0, 1
	.byte	8, 1, 0
	.byte	1, 6, 1
	.byte	3, 3, 1
	.byte	4, 3, 0
	.byte	1, 8, 1
	.byte	3, 4, 1
	.byte	4, 4, 0
	.byte	1, 9, 1
	.byte	12, 0, 1
	.byte	13, 0, 1
	.byte	14, 0, 1
	.byte	8, 2, 0
	.byte	1, 10, 1
	.byte	3, 5, 1
	.byte	4, 5, 0
	.byte	1, 12, 1
	.byte	3, 6, 1
	.byte	4, 6, 0
	.byte	1, 13, 1
	.byte	15, 0, 1
	.byte	16, 0, 1
	.byte	8, 3, 0
	.byte	1, 14, 1
	.byte	3, 7, 1
	.byte	4, 7, 1
	.byte	17, 0, 0
	.size	PROG, 135

	.protected	BGTAB
	.type	BGTAB,@object
	.globl	BGTAB
	.p2align	4, 0x0
